# MLA loop: QK^T K-fragment reads double-buffered one group ahead (two 16-reg fragment sets)
# speedup vs baseline: 1.0015x; 1.0015x over previous
; #define SBAR() __builtin_amdgcn_sched_barrier(0)
; template <int MODE> __device__ __forceinline__ void partialSM(f32x16& p0, f32x16& p1, float& m_reg, float& mn, float& alpha, float C, float thr, const float* auxk, float pq, float nsl, int hi) {
;     ...
;   float pmax = p0[0];
; #pragma unroll
;   for (int r = 1; r < 16; ++r) pmax = fmaxf(pmax, p0[r]);
; #pragma unroll
;   for (int r = 0; r < 16; ++r) pmax = fmaxf(pmax, p1[r]);
;   { auto rr = __builtin_amdgcn_permlane32_swap(__float_as_uint(pmax), __float_as_uint(pmax), false, false);
;     pmax = fmaxf(__uint_as_float(rr[0]), __uint_as_float(rr[1])); }
;   if (__builtin_expect(__all(pmax - m_reg <= thr), 1)) { mn = m_reg; alpha = 1.f; }
;   else { mn = fmaxf(m_reg, pmax); alpha = __builtin_amdgcn_exp2f((m_reg - mn) * C); m_reg = mn; }
;     ...
;   const int sw = (r32 & 7) << 4; const char* k0p = Ks + r32 * ROWB; const char* k1p = Ks + (32 + r32) * ROWB;
; #pragma unroll
;   for (int h2 = 0; h2 < DQK / 32; ++h2) { const int cba = (((2 * h2) * 16 + hi * 8) * 2) ^ sw, cbb = (((2 * h2 + 1) * 16 + hi * 8) * 2) ^ sw;
;     const bf16x8 a0 = *reinterpret_cast<const bf16x8*>(k0p + cba), a1 = *reinterpret_cast<const bf16x8*>(k1p + cba);
;     const bf16x8 b0 = *reinterpret_cast<const bf16x8*>(k0p + cbb), b1 = *reinterpret_cast<const bf16x8*>(k1p + cbb);
;     SBAR();
;     p0 = __builtin_amdgcn_mfma_f32_32x32x16_bf16(a0, qr[2 * h2], p0, 0, 0, 0);
;     p1 = __builtin_amdgcn_mfma_f32_32x32x16_bf16(a1, qr[2 * h2], p1, 0, 0, 0);
;     p0 = __builtin_amdgcn_mfma_f32_32x32x16_bf16(b0, qr[2 * h2 + 1], p0, 0, 0, 0);
;     p1 = __builtin_amdgcn_mfma_f32_32x32x16_bf16(b1, qr[2 * h2 + 1], p1, 0, 0, 0);
;     SBAR(); }
.LBB0_1020:
	s_mul_i32 s4, s68, 0x6000
	v_add_u32_e32 v192, s4, v159
	v_add_u32_e32 v210, v192, v161
	v_add_u32_e32 v211, v192, v162
	ds_read_b128 v[176:179], v210 offset:49152
	ds_read_b128 v[180:183], v210 offset:61440
	ds_read_b128 v[184:187], v211 offset:49152
	ds_read_b128 v[188:191], v211 offset:61440
	v_add_u32_e32 v210, v192, v163
	v_add_u32_e32 v211, v192, v164
	ds_read_b128 v[194:197], v210 offset:49152
	ds_read_b128 v[198:201], v210 offset:61440
	ds_read_b128 v[202:205], v211 offset:49152
	ds_read_b128 v[206:209], v211 offset:61440
	s_waitcnt lgkmcnt(4)
	v_mfma_f32_32x32x16_bf16 v[82:97], v[176:179], v[98:101], 0
	v_mfma_f32_32x32x16_bf16 v[66:81], v[180:183], v[98:101], 0
	v_mfma_f32_32x32x16_bf16 v[82:97], v[184:187], v[102:105], v[82:97]
	v_mfma_f32_32x32x16_bf16 v[66:81], v[188:191], v[102:105], v[66:81]
	v_add_u32_e32 v210, v192, v165
	v_add_u32_e32 v211, v192, v166
	ds_read_b128 v[176:179], v210 offset:49152
	ds_read_b128 v[180:183], v210 offset:61440
	ds_read_b128 v[184:187], v211 offset:49152
	ds_read_b128 v[188:191], v211 offset:61440
	s_waitcnt lgkmcnt(4)
	v_mfma_f32_32x32x16_bf16 v[82:97], v[194:197], v[106:109], v[82:97]
	v_mfma_f32_32x32x16_bf16 v[66:81], v[198:201], v[106:109], v[66:81]
	v_mfma_f32_32x32x16_bf16 v[82:97], v[202:205], v[110:113], v[82:97]
	v_mfma_f32_32x32x16_bf16 v[66:81], v[206:209], v[110:113], v[66:81]
	v_add_u32_e32 v210, v192, v167
	v_add_u32_e32 v211, v192, v168
	ds_read_b128 v[194:197], v210 offset:49152
	ds_read_b128 v[198:201], v210 offset:61440
	ds_read_b128 v[202:205], v211 offset:49152
	ds_read_b128 v[206:209], v211 offset:61440
	s_waitcnt lgkmcnt(4)
	v_mfma_f32_32x32x16_bf16 v[82:97], v[176:179], v[114:117], v[82:97]
	v_mfma_f32_32x32x16_bf16 v[66:81], v[180:183], v[114:117], v[66:81]
	v_mfma_f32_32x32x16_bf16 v[82:97], v[184:187], v[118:121], v[82:97]
	v_mfma_f32_32x32x16_bf16 v[66:81], v[188:191], v[118:121], v[66:81]
	v_add_u32_e32 v210, v192, v169
	v_add_u32_e32 v211, v192, v171
	ds_read_b128 v[176:179], v210 offset:49152
	ds_read_b128 v[180:183], v210 offset:61440
	ds_read_b128 v[184:187], v211 offset:49152
	ds_read_b128 v[188:191], v211 offset:61440
	s_waitcnt lgkmcnt(4)
	v_mfma_f32_32x32x16_bf16 v[82:97], v[194:197], v[122:125], v[82:97]
	v_mfma_f32_32x32x16_bf16 v[66:81], v[198:201], v[122:125], v[66:81]
	v_mfma_f32_32x32x16_bf16 v[82:97], v[202:205], v[126:129], v[82:97]
	v_mfma_f32_32x32x16_bf16 v[66:81], v[206:209], v[126:129], v[66:81]
	v_add_u32_e32 v210, v192, v172
	v_add_u32_e32 v211, v192, v173
	ds_read_b128 v[194:197], v210 offset:49152
	ds_read_b128 v[198:201], v210 offset:61440
	ds_read_b128 v[202:205], v211 offset:49152
	ds_read_b128 v[206:209], v211 offset:61440
	s_waitcnt lgkmcnt(4)
	v_mfma_f32_32x32x16_bf16 v[82:97], v[176:179], v[130:133], v[82:97]
	v_mfma_f32_32x32x16_bf16 v[66:81], v[180:183], v[130:133], v[66:81]
	v_mfma_f32_32x32x16_bf16 v[82:97], v[184:187], v[134:137], v[82:97]
	v_mfma_f32_32x32x16_bf16 v[66:81], v[188:191], v[134:137], v[66:81]
	s_waitcnt lgkmcnt(0)
	v_mfma_f32_32x32x16_bf16 v[82:97], v[194:197], v[138:141], v[82:97]
	v_mfma_f32_32x32x16_bf16 v[66:81], v[198:201], v[138:141], v[66:81]
	v_mfma_f32_32x32x16_bf16 v[82:97], v[202:205], v[142:145], v[82:97]
	v_mfma_f32_32x32x16_bf16 v[66:81], v[206:209], v[142:145], v[66:81]
	s_nop 10
	v_max_f32_e32 v176, v83, v83
	v_max_f32_e32 v177, v82, v82
	v_max_f32_e32 v176, v177, v176
	v_max3_f32 v176, v176, v84, v85
	v_max3_f32 v176, v176, v86, v87
	v_max3_f32 v176, v176, v88, v89
	v_max3_f32 v176, v176, v90, v91
	v_max3_f32 v176, v176, v92, v93
	v_max3_f32 v176, v176, v94, v95
	v_max3_f32 v176, v176, v96, v97
	v_max3_f32 v176, v176, v66, v67
	v_max3_f32 v176, v176, v68, v69
	v_max3_f32 v176, v176, v70, v71
	v_max3_f32 v176, v176, v72, v73
	v_max3_f32 v176, v176, v74, v75
	v_max3_f32 v176, v176, v76, v77
	v_max3_f32 v176, v176, v78, v79
	v_max3_f32 v176, v176, v80, v81
	v_mov_b32_e32 v177, v176
	s_nop 1
	v_permlane32_swap_b32_e32 v176, v177
	v_max_f32_e32 v177, v177, v177
	v_max_f32_e32 v176, v176, v176
	v_max_f32_e32 v176, v176, v177
	v_sub_f32_e32 v177, v176, v175
	s_mov_b32 s4, 0x42ddb3d8
	v_cmp_ge_f32_e32 vcc, s4, v177
	v_max_f32_e32 v177, v175, v175
	v_max_f32_e32 v177, v177, v176
	v_sub_f32_e32 v176, v175, v177
	v_mul_f32_e32 v176, 0x3dd53b94, v176
	v_exp_f32_e32 v176, v176
	s_cmp_eq_u64 vcc, exec
	s_cselect_b64 s[4:5], -1, 0
	v_cndmask_b32_e64 v176, v176, 1.0, s[4:5]
	v_cmp_gt_f32_e32 vcc, 1.0, v176
	s_cbranch_vccz .LBB0_1024
	s_and_saveexec_b64 s[38:39], s[2:3]
	ds_write_b32 v170, v176 offset:128
	s_or_b64 exec, exec, s[38:39]
	s_waitcnt lgkmcnt(0)
	v_add_u32_e32 v190, s63, v160
	ds_read_b128 v[178:181], v190 offset:224
	ds_read_b128 v[182:185], v190 offset:192
	ds_read_b128 v[186:189], v190 offset:160
	ds_read_b128 v[190:193], v190 offset:128
	s_waitcnt lgkmcnt(3)
	v_pk_mul_f32 v[62:63], v[62:63], v[178:179]
	s_waitcnt lgkmcnt(2)
	v_pk_mul_f32 v[58:59], v[58:59], v[182:183]
	s_waitcnt lgkmcnt(1)
	v_pk_mul_f32 v[54:55], v[54:55], v[186:187]
	v_pk_mul_f32 v[64:65], v[64:65], v[180:181]
	v_pk_mul_f32 v[60:61], v[60:61], v[184:185]
	v_pk_mul_f32 v[56:57], v[56:57], v[188:189]
	s_waitcnt lgkmcnt(0)
	v_pk_mul_f32 v[52:53], v[52:53], v[192:193]
	v_pk_mul_f32 v[50:51], v[50:51], v[190:191]
	v_pk_mul_f32 v[46:47], v[46:47], v[178:179]
	v_pk_mul_f32 v[42:43], v[42:43], v[182:183]
	v_pk_mul_f32 v[38:39], v[38:39], v[186:187]
	v_pk_mul_f32 v[48:49], v[48:49], v[180:181]
	v_pk_mul_f32 v[44:45], v[44:45], v[184:185]
	v_pk_mul_f32 v[40:41], v[40:41], v[188:189]
	v_pk_mul_f32 v[36:37], v[36:37], v[192:193]
	v_pk_mul_f32 v[34:35], v[34:35], v[190:191]
	v_pk_mul_f32 v[30:31], v[30:31], v[178:179]
	v_pk_mul_f32 v[26:27], v[26:27], v[182:183]
	v_pk_mul_f32 v[22:23], v[22:23], v[186:187]
	v_pk_mul_f32 v[32:33], v[32:33], v[180:181]
	v_pk_mul_f32 v[28:29], v[28:29], v[184:185]
	v_pk_mul_f32 v[24:25], v[24:25], v[188:189]
	v_pk_mul_f32 v[20:21], v[20:21], v[192:193]
	v_pk_mul_f32 v[18:19], v[18:19], v[190:191]
	v_pk_mul_f32 v[14:15], v[14:15], v[178:179]
	v_pk_mul_f32 v[10:11], v[10:11], v[182:183]
	v_pk_mul_f32 v[6:7], v[6:7], v[186:187]
	v_pk_mul_f32 v[16:17], v[16:17], v[180:181]
	v_pk_mul_f32 v[12:13], v[12:13], v[184:185]
	v_pk_mul_f32 v[8:9], v[8:9], v[188:189]
	v_pk_mul_f32 v[4:5], v[4:5], v[192:193]
	v_pk_mul_f32 v[2:3], v[2:3], v[190:191]
